# P0 ln_in_rows: gate reduce-scatter tree and wsum butterflies replaced by DPP wave reductions + readlane/writelane
# baseline (speedup 1.0000x reference)
; DI unsigned pack2(float a, float b) { const f32x2 v = {a, b}; return __builtin_bit_cast(unsigned, __builtin_convertvector(v, bf16v2)); }
; DI float wsum(float v) { for (int o = 32; o; o >>= 1) v += __shfl_xor(v, o); return v; }
; DI void ln_in_rows(const float* __restrict__ src, const float* __restrict__ g, const float* __restrict__ bta, const float* __restrict__ w_in, u16* __restrict__ dst, float* __restrict__ G, float* Wg) {
;     ...
;     for (int i = 0; i < 4; ++i) { v[i] = nv[i]; s += v[i].x + v[i].y + v[i].z + v[i].w; }
;     { const int nrow = row + gridDim.x * 8; if (nrow < T_TOK) for (int i = 0; i < 4; ++i) nv[i] = *(const float4*)(src + (size_t)nrow * 1024 + i * 256 + lane * 4); }
;     const float mu = wsum(s) * (1.f / 1024.f);
;     float q = 0.f;
;     for (int i = 0; i < 4; ++i) { float a = v[i].x - mu, b = v[i].y - mu, c = v[i].z - mu, d = v[i].w - mu; q += a * a + b * b + c * c + d * d; }
;     const float rstd = rsqrtf(wsum(q) * (1.f / 1024.f) + LN_EPS);
;     float pg[8];
; #pragma unroll
;     for (int j = 0; j < 8; ++j) pg[j] = 0.f;
; #pragma unroll
;     for (int i = 0; i < 4; ++i) {
;       const int c0 = i * 256 + lane * 4;
;       float4 gg = *(const float4*)(g + c0), bb = *(const float4*)(bta + c0);
;       float y[4];
;       y[0] = (v[i].x - mu) * rstd * gg.x + bb.x; y[1] = (v[i].y - mu) * rstd * gg.y + bb.y; y[2] = (v[i].z - mu) * rstd * gg.z + bb.z; y[3] = (v[i].w - mu) * rstd * gg.w + bb.w;
;       uint2 o; o.x = pack2(y[0], y[1]); o.y = pack2(y[2], y[3]);
;       *(uint2*)(dst + (size_t)row * 1024 + c0) = o;
; #pragma unroll
;       for (int e = 0; e < 4; ++e) {
;         const float4 w0 = *(const float4*)(Wg + (c0 + e) * 8), w1 = *(const float4*)(Wg + (c0 + e) * 8 + 4);
;         pg[0] += y[e] * w0.x; pg[1] += y[e] * w0.y; pg[2] += y[e] * w0.z; pg[3] += y[e] * w0.w;
;         pg[4] += y[e] * w1.x; pg[5] += y[e] * w1.y; pg[6] += y[e] * w1.z; pg[7] += y[e] * w1.w;
.LBB0_170:
	s_or_b64 exec, exec, s[10:11]
	v_add_f32_e32 v195, v190, v191
	v_add_f32_e32 v195, v195, v192
	v_add_f32_e32 v217, v186, v187
	v_add_f32_e32 v195, v195, v193
	v_add_f32_e32 v217, v217, v188
	v_add_f32_e32 v195, 0, v195
	v_add_f32_e32 v217, v217, v189
	v_add_f32_e32 v195, v195, v217
	v_add_f32_e32 v217, v182, v183
	v_add_f32_e32 v217, v217, v184
	v_add_f32_e32 v217, v217, v185
	v_add_f32_e32 v195, v195, v217
	v_add_f32_e32 v217, v178, v179
	v_add_f32_e32 v217, v217, v180
	v_add_f32_e32 v217, v217, v181
	v_add_f32_e32 v195, v195, v217
	s_nop 1
	v_add_f32_dpp v195, v195, v195 row_shr:1 row_mask:0xf bank_mask:0xf
	s_nop 1
	v_add_f32_dpp v195, v195, v195 row_shr:2 row_mask:0xf bank_mask:0xf
	s_nop 1
	v_add_f32_dpp v195, v195, v195 row_shr:4 row_mask:0xf bank_mask:0xf
	s_nop 1
	v_add_f32_dpp v195, v195, v195 row_shr:8 row_mask:0xf bank_mask:0xf
	s_nop 1
	v_add_f32_dpp v195, v195, v195 row_bcast:15 row_mask:0xa bank_mask:0xf
	s_nop 1
	v_add_f32_dpp v195, v195, v195 row_bcast:31 row_mask:0xc bank_mask:0xf
	s_nop 0
	v_readlane_b32 s72, v195, 63
	s_nop 1
	v_mov_b32_e32 v195, s72
	v_mul_f32_e32 v234, 0x3a800000, v195
	v_pk_add_f32 v[190:191], v[190:191], v[234:235] op_sel_hi:[1,0] neg_lo:[0,1] neg_hi:[0,1]
	v_pk_add_f32 v[186:187], v[186:187], v[234:235] op_sel_hi:[1,0] neg_lo:[0,1] neg_hi:[0,1]
	v_mov_b32_e32 v240, v191
	v_mov_b32_e32 v241, v187
	v_pk_add_f32 v[192:193], v[192:193], v[234:235] op_sel_hi:[1,0] neg_lo:[0,1] neg_hi:[0,1]
	v_pk_add_f32 v[188:189], v[188:189], v[234:235] op_sel_hi:[1,0] neg_lo:[0,1] neg_hi:[0,1]
	v_pk_add_f32 v[182:183], v[182:183], v[234:235] op_sel_hi:[1,0] neg_lo:[0,1] neg_hi:[0,1]
	v_pk_add_f32 v[236:237], v[180:181], v[234:235] op_sel_hi:[1,0] neg_lo:[0,1] neg_hi:[0,1]
	v_pk_add_f32 v[180:181], v[178:179], v[234:235] op_sel_hi:[1,0] neg_lo:[0,1] neg_hi:[0,1]
	v_mov_b32_e32 v238, v190
	v_mov_b32_e32 v239, v186
	v_pk_mul_f32 v[240:241], v[240:241], v[240:241]
	v_mov_b32_e32 v178, v192
	v_mov_b32_e32 v179, v188
	v_pk_fma_f32 v[238:239], v[238:239], v[238:239], v[240:241]
	v_mov_b32_e32 v240, v181
	v_mov_b32_e32 v241, v183
	v_pk_add_f32 v[184:185], v[184:185], v[234:235] op_sel_hi:[1,0] neg_lo:[0,1] neg_hi:[0,1]
	v_pk_fma_f32 v[178:179], v[178:179], v[178:179], v[238:239]
	v_mov_b32_e32 v238, v180
	v_mov_b32_e32 v239, v182
	v_pk_mul_f32 v[240:241], v[240:241], v[240:241]
	v_mov_b32_e32 v234, v193
	v_mov_b32_e32 v235, v189
	v_mov_b32_e32 v242, v236
	v_mov_b32_e32 v243, v184
	v_pk_fma_f32 v[238:239], v[238:239], v[238:239], v[240:241]
	v_pk_fma_f32 v[178:179], v[234:235], v[234:235], v[178:179]
	v_mov_b32_e32 v234, v237
	v_mov_b32_e32 v235, v185
	v_pk_fma_f32 v[238:239], v[242:243], v[242:243], v[238:239]
	v_add_f32_e32 v178, v178, v179
	v_pk_fma_f32 v[234:235], v[234:235], v[234:235], v[238:239]
	v_ashrrev_i32_e32 v195, 31, v194
	v_add_f32_e32 v178, v235, v178
	v_add_f32_e32 v178, v234, v178
	s_nop 1
	v_add_f32_dpp v178, v178, v178 row_shr:1 row_mask:0xf bank_mask:0xf
	s_nop 1
	v_add_f32_dpp v178, v178, v178 row_shr:2 row_mask:0xf bank_mask:0xf
	s_nop 1
	v_add_f32_dpp v178, v178, v178 row_shr:4 row_mask:0xf bank_mask:0xf
	s_nop 1
	v_add_f32_dpp v178, v178, v178 row_shr:8 row_mask:0xf bank_mask:0xf
	s_nop 1
	v_add_f32_dpp v178, v178, v178 row_bcast:15 row_mask:0xa bank_mask:0xf
	s_nop 1
	v_add_f32_dpp v178, v178, v178 row_bcast:31 row_mask:0xc bank_mask:0xf
	s_nop 0
	v_readlane_b32 s73, v178, 63
	s_nop 1
	v_mov_b32_e32 v178, s73
	v_fmamk_f32 v178, v178, 0x3a800000, v215
	v_mul_f32_e32 v179, 0x4b800000, v178
	v_cmp_gt_f32_e64 s[8:9], s12, v178
	s_nop 1
	v_cndmask_b32_e64 v178, v178, v179, s[8:9]
	v_rsq_f32_e32 v217, v178
	v_lshlrev_b64 v[178:179], 11, v[194:195]
	v_lshl_add_u64 v[178:179], v[230:231], 0, v[178:179]
	v_mul_f32_e32 v219, 0x45800000, v217
	v_cndmask_b32_e64 v238, v217, v219, s[8:9]
	v_pk_mul_f32 v[190:191], v[190:191], v[238:239] op_sel_hi:[1,0]
	v_pk_mul_f32 v[234:235], v[192:193], v[238:239] op_sel_hi:[1,0]
	v_pk_mul_f32 v[182:183], v[182:183], v[238:239] op_sel_hi:[1,0]
	s_waitcnt vmcnt(6)
	v_pk_fma_f32 v[192:193], v[2:3], v[190:191], v[6:7]
	v_pk_mul_f32 v[240:241], v[184:185], v[238:239] op_sel_hi:[1,0]
	s_waitcnt vmcnt(2)
	v_pk_fma_f32 v[184:185], v[18:19], v[182:183], v[22:23]
	v_pk_mul_f32 v[182:183], v[236:237], v[238:239] op_sel_hi:[1,0]
	v_pk_fma_f32 v[236:237], v[34:35], v[192:193], 0 op_sel_hi:[1,0,0]
	v_pk_mul_f32 v[186:187], v[186:187], v[238:239] op_sel_hi:[1,0]
	v_pk_mul_f32 v[188:189], v[188:189], v[238:239] op_sel_hi:[1,0]
	v_pk_mul_f32 v[180:181], v[180:181], v[238:239] op_sel_hi:[1,0]
	v_pk_fma_f32 v[234:235], v[4:5], v[234:235], v[8:9]
	v_pk_fma_f32 v[236:237], v[42:43], v[192:193], v[236:237] op_sel:[0,1,0]
	v_pk_fma_f32 v[238:239], v[36:37], v[192:193], 0 op_sel_hi:[1,0,0]
	v_pk_fma_f32 v[236:237], v[50:51], v[234:235], v[236:237] op_sel_hi:[1,0,1]
	v_pk_fma_f32 v[238:239], v[44:45], v[192:193], v[238:239] op_sel:[0,1,0]
	v_pk_fma_f32 v[190:191], v[10:11], v[186:187], v[14:15]
	v_pk_fma_f32 v[186:187], v[20:21], v[240:241], v[24:25]
	v_pk_fma_f32 v[236:237], v[58:59], v[234:235], v[236:237] op_sel:[0,1,0]
	v_pk_fma_f32 v[238:239], v[52:53], v[234:235], v[238:239] op_sel_hi:[1,0,1]
	v_pk_fma_f32 v[240:241], v[38:39], v[192:193], 0 op_sel_hi:[1,0,0]
	v_pk_fma_f32 v[236:237], v[66:67], v[190:191], v[236:237] op_sel_hi:[1,0,1]
	v_pk_fma_f32 v[238:239], v[60:61], v[234:235], v[238:239] op_sel:[0,1,0]
	v_pk_fma_f32 v[240:241], v[46:47], v[192:193], v[240:241] op_sel:[0,1,0]
	v_pk_fma_f32 v[188:189], v[12:13], v[188:189], v[16:17]
	v_pk_fma_f32 v[236:237], v[74:75], v[190:191], v[236:237] op_sel:[0,1,0]
	v_pk_fma_f32 v[238:239], v[68:69], v[190:191], v[238:239] op_sel_hi:[1,0,1]
; DI void ln_in_rows(const float* __restrict__ src, const float* __restrict__ g, const float* __restrict__ bta, const float* __restrict__ w_in, u16* __restrict__ dst, float* __restrict__ G, float* Wg) {
;     ...
; #pragma unroll
;       for (int e = 0; e < 4; ++e) {
;         const float4 w0 = *(const float4*)(Wg + (c0 + e) * 8), w1 = *(const float4*)(Wg + (c0 + e) * 8 + 4);
;         pg[0] += y[e] * w0.x; pg[1] += y[e] * w0.y; pg[2] += y[e] * w0.z; pg[3] += y[e] * w0.w;
;         pg[4] += y[e] * w1.x; pg[5] += y[e] * w1.y; pg[6] += y[e] * w1.z; pg[7] += y[e] * w1.w;
	v_pk_fma_f32 v[240:241], v[54:55], v[234:235], v[240:241] op_sel_hi:[1,0,1]
	v_pk_fma_f32 v[242:243], v[40:41], v[192:193], 0 op_sel_hi:[1,0,0]
	v_pk_fma_f32 v[236:237], v[82:83], v[188:189], v[236:237] op_sel_hi:[1,0,1]
	v_pk_fma_f32 v[238:239], v[76:77], v[190:191], v[238:239] op_sel:[0,1,0]
	v_pk_fma_f32 v[240:241], v[62:63], v[234:235], v[240:241] op_sel:[0,1,0]
	v_pk_fma_f32 v[242:243], v[48:49], v[192:193], v[242:243] op_sel:[0,1,0]
	v_pk_fma_f32 v[236:237], v[90:91], v[188:189], v[236:237] op_sel:[0,1,0]
	v_pk_fma_f32 v[238:239], v[84:85], v[188:189], v[238:239] op_sel_hi:[1,0,1]
	v_pk_fma_f32 v[240:241], v[70:71], v[190:191], v[240:241] op_sel_hi:[1,0,1]
	v_pk_fma_f32 v[242:243], v[56:57], v[234:235], v[242:243] op_sel_hi:[1,0,1]
	v_pk_fma_f32 v[236:237], v[98:99], v[184:185], v[236:237] op_sel_hi:[1,0,1]
	v_pk_fma_f32 v[238:239], v[92:93], v[188:189], v[238:239] op_sel:[0,1,0]
	v_pk_fma_f32 v[240:241], v[78:79], v[190:191], v[240:241] op_sel:[0,1,0]
	v_pk_fma_f32 v[242:243], v[64:65], v[234:235], v[242:243] op_sel:[0,1,0]
	v_pk_fma_f32 v[236:237], v[106:107], v[184:185], v[236:237] op_sel:[0,1,0]
	v_pk_fma_f32 v[238:239], v[100:101], v[184:185], v[238:239] op_sel_hi:[1,0,1]
	v_pk_fma_f32 v[240:241], v[86:87], v[188:189], v[240:241] op_sel_hi:[1,0,1]
	v_pk_fma_f32 v[242:243], v[72:73], v[190:191], v[242:243] op_sel_hi:[1,0,1]
	v_pk_fma_f32 v[236:237], v[114:115], v[186:187], v[236:237] op_sel_hi:[1,0,1]
	v_pk_fma_f32 v[238:239], v[108:109], v[184:185], v[238:239] op_sel:[0,1,0]
	v_pk_fma_f32 v[240:241], v[94:95], v[188:189], v[240:241] op_sel:[0,1,0]
	v_pk_fma_f32 v[242:243], v[80:81], v[190:191], v[242:243] op_sel:[0,1,0]
	s_waitcnt vmcnt(0)
; DI unsigned pack2(float a, float b) { const f32x2 v = {a, b}; return __builtin_bit_cast(unsigned, __builtin_convertvector(v, bf16v2)); }
; DI void ln_in_rows(const float* __restrict__ src, const float* __restrict__ g, const float* __restrict__ bta, const float* __restrict__ w_in, u16* __restrict__ dst, float* __restrict__ G, float* Wg) {
;     ...
;       uint2 o; o.x = pack2(y[0], y[1]); o.y = pack2(y[2], y[3]);
;       *(uint2*)(dst + (size_t)row * 1024 + c0) = o;
; #pragma unroll
;       for (int e = 0; e < 4; ++e) {
;         const float4 w0 = *(const float4*)(Wg + (c0 + e) * 8), w1 = *(const float4*)(Wg + (c0 + e) * 8 + 4);
;         pg[0] += y[e] * w0.x; pg[1] += y[e] * w0.y; pg[2] += y[e] * w0.z; pg[3] += y[e] * w0.w;
;         pg[4] += y[e] * w1.x; pg[5] += y[e] * w1.y; pg[6] += y[e] * w1.z; pg[7] += y[e] * w1.w;
;       }
;     }
; #pragma unroll
;     for (int off = 32; off >= 8; off >>= 1) {
;       const bool up = (lane & off) != 0;
;       const int nkeep = off >> 3;
; #pragma unroll
;       for (int i = 0; i < 4; ++i) if (i < nkeep) {
;         const float send = up ? pg[i] : pg[i + nkeep];
;         const float keep = up ? pg[i + nkeep] : pg[i];
;         pg[i] = keep + __shfl_xor(send, off);
;       }
;     }
;     float tot = pg[0];
;     tot += __shfl_xor(tot, 4); tot += __shfl_xor(tot, 2); tot += __shfl_xor(tot, 1);
;     if ((lane & 7) == 0) G[(size_t)row * 8 + (lane >> 3)] = tot;
	v_pk_fma_f32 v[180:181], v[26:27], v[180:181], v[30:31]
	v_pk_fma_f32 v[236:237], v[122:123], v[186:187], v[236:237] op_sel:[0,1,0]
	v_pk_fma_f32 v[238:239], v[116:117], v[186:187], v[238:239] op_sel_hi:[1,0,1]
	v_pk_fma_f32 v[240:241], v[102:103], v[184:185], v[240:241] op_sel_hi:[1,0,1]
	v_pk_fma_f32 v[242:243], v[88:89], v[188:189], v[242:243] op_sel_hi:[1,0,1]
	v_pk_fma_f32 v[236:237], v[130:131], v[180:181], v[236:237] op_sel_hi:[1,0,1]
	v_pk_fma_f32 v[238:239], v[124:125], v[186:187], v[238:239] op_sel:[0,1,0]
	v_pk_fma_f32 v[240:241], v[110:111], v[184:185], v[240:241] op_sel:[0,1,0]
	v_pk_fma_f32 v[242:243], v[96:97], v[188:189], v[242:243] op_sel:[0,1,0]
	v_pk_fma_f32 v[182:183], v[28:29], v[182:183], v[32:33]
	v_pk_fma_f32 v[236:237], v[138:139], v[180:181], v[236:237] op_sel:[0,1,0]
	v_pk_fma_f32 v[238:239], v[132:133], v[180:181], v[238:239] op_sel_hi:[1,0,1]
	v_pk_fma_f32 v[240:241], v[118:119], v[186:187], v[240:241] op_sel_hi:[1,0,1]
	v_pk_fma_f32 v[242:243], v[104:105], v[184:185], v[242:243] op_sel_hi:[1,0,1]
	v_pk_fma_f32 v[236:237], v[146:147], v[182:183], v[236:237] op_sel_hi:[1,0,1]
	v_pk_fma_f32 v[238:239], v[140:141], v[180:181], v[238:239] op_sel:[0,1,0]
	v_pk_fma_f32 v[240:241], v[126:127], v[186:187], v[240:241] op_sel:[0,1,0]
	v_pk_fma_f32 v[242:243], v[112:113], v[184:185], v[242:243] op_sel:[0,1,0]
	v_pk_fma_f32 v[236:237], v[154:155], v[182:183], v[236:237] op_sel:[0,1,0]
	v_pk_fma_f32 v[238:239], v[148:149], v[182:183], v[238:239] op_sel_hi:[1,0,1]
	v_pk_fma_f32 v[240:241], v[180:181], v[134:135], v[240:241] op_sel_hi:[0,1,1]
	v_pk_fma_f32 v[242:243], v[120:121], v[186:187], v[242:243] op_sel_hi:[1,0,1]
	v_pk_fma_f32 v[238:239], v[156:157], v[182:183], v[238:239] op_sel:[0,1,0]
	v_pk_fma_f32 v[240:241], v[180:181], v[142:143], v[240:241] op_sel:[1,0,0]
	v_pk_fma_f32 v[242:243], v[128:129], v[186:187], v[242:243] op_sel:[0,1,0]
	v_pk_fma_f32 v[240:241], v[182:183], v[150:151], v[240:241] op_sel_hi:[0,1,1]
	v_pk_fma_f32 v[242:243], v[180:181], v[136:137], v[242:243] op_sel_hi:[0,1,1]
	v_pk_fma_f32 v[240:241], v[182:183], v[158:159], v[240:241] op_sel:[1,0,0]
	v_pk_fma_f32 v[242:243], v[180:181], v[144:145], v[242:243] op_sel:[1,0,0]
	v_pk_fma_f32 v[242:243], v[182:183], v[152:153], v[242:243] op_sel_hi:[0,1,1]
	v_pk_fma_f32 v[242:243], v[182:183], v[160:161], v[242:243] op_sel:[1,0,0]
	v_cvt_pk_bf16_f32 v192, v192, v193
	v_cvt_pk_bf16_f32 v193, v234, v235
	global_store_dwordx2 v[178:179], v[192:193], off
	v_cvt_pk_bf16_f32 v190, v190, v191
	v_cvt_pk_bf16_f32 v191, v188, v189
	v_cvt_pk_bf16_f32 v188, v184, v185
	v_cvt_pk_bf16_f32 v189, v186, v187
	v_cvt_pk_bf16_f32 v180, v180, v181
	v_cvt_pk_bf16_f32 v181, v182, v183
	global_store_dwordx2 v[178:179], v[190:191], off offset:512
	global_store_dwordx2 v[178:179], v[188:189], off offset:1024
	global_store_dwordx2 v[178:179], v[180:181], off offset:1536
	v_add_f32_dpp v236, v236, v236 row_shr:1 row_mask:0xf bank_mask:0xf
	v_add_f32_dpp v237, v237, v237 row_shr:1 row_mask:0xf bank_mask:0xf
	v_add_f32_dpp v238, v238, v238 row_shr:1 row_mask:0xf bank_mask:0xf
	v_add_f32_dpp v239, v239, v239 row_shr:1 row_mask:0xf bank_mask:0xf
	v_add_f32_dpp v240, v240, v240 row_shr:1 row_mask:0xf bank_mask:0xf
	v_add_f32_dpp v241, v241, v241 row_shr:1 row_mask:0xf bank_mask:0xf
	v_add_f32_dpp v242, v242, v242 row_shr:1 row_mask:0xf bank_mask:0xf
	v_add_f32_dpp v243, v243, v243 row_shr:1 row_mask:0xf bank_mask:0xf
	v_add_f32_dpp v236, v236, v236 row_shr:2 row_mask:0xf bank_mask:0xf
	v_add_f32_dpp v237, v237, v237 row_shr:2 row_mask:0xf bank_mask:0xf
	v_add_f32_dpp v238, v238, v238 row_shr:2 row_mask:0xf bank_mask:0xf
	v_add_f32_dpp v239, v239, v239 row_shr:2 row_mask:0xf bank_mask:0xf
	v_add_f32_dpp v240, v240, v240 row_shr:2 row_mask:0xf bank_mask:0xf
	v_add_f32_dpp v241, v241, v241 row_shr:2 row_mask:0xf bank_mask:0xf
	v_add_f32_dpp v242, v242, v242 row_shr:2 row_mask:0xf bank_mask:0xf
	v_add_f32_dpp v243, v243, v243 row_shr:2 row_mask:0xf bank_mask:0xf
	v_add_f32_dpp v236, v236, v236 row_shr:4 row_mask:0xf bank_mask:0xf
	v_add_f32_dpp v237, v237, v237 row_shr:4 row_mask:0xf bank_mask:0xf
	v_add_f32_dpp v238, v238, v238 row_shr:4 row_mask:0xf bank_mask:0xf
	v_add_f32_dpp v239, v239, v239 row_shr:4 row_mask:0xf bank_mask:0xf
	v_add_f32_dpp v240, v240, v240 row_shr:4 row_mask:0xf bank_mask:0xf
	v_add_f32_dpp v241, v241, v241 row_shr:4 row_mask:0xf bank_mask:0xf
	v_add_f32_dpp v242, v242, v242 row_shr:4 row_mask:0xf bank_mask:0xf
	v_add_f32_dpp v243, v243, v243 row_shr:4 row_mask:0xf bank_mask:0xf
	v_add_f32_dpp v236, v236, v236 row_shr:8 row_mask:0xf bank_mask:0xf
	v_add_f32_dpp v237, v237, v237 row_shr:8 row_mask:0xf bank_mask:0xf
	v_add_f32_dpp v238, v238, v238 row_shr:8 row_mask:0xf bank_mask:0xf
	v_add_f32_dpp v239, v239, v239 row_shr:8 row_mask:0xf bank_mask:0xf
	v_add_f32_dpp v240, v240, v240 row_shr:8 row_mask:0xf bank_mask:0xf
	v_add_f32_dpp v241, v241, v241 row_shr:8 row_mask:0xf bank_mask:0xf
	v_add_f32_dpp v242, v242, v242 row_shr:8 row_mask:0xf bank_mask:0xf
	v_add_f32_dpp v243, v243, v243 row_shr:8 row_mask:0xf bank_mask:0xf
	v_add_f32_dpp v236, v236, v236 row_bcast:15 row_mask:0xa bank_mask:0xf
	v_add_f32_dpp v237, v237, v237 row_bcast:15 row_mask:0xa bank_mask:0xf
	v_add_f32_dpp v238, v238, v238 row_bcast:15 row_mask:0xa bank_mask:0xf
	v_add_f32_dpp v239, v239, v239 row_bcast:15 row_mask:0xa bank_mask:0xf
	v_add_f32_dpp v240, v240, v240 row_bcast:15 row_mask:0xa bank_mask:0xf
	v_add_f32_dpp v241, v241, v241 row_bcast:15 row_mask:0xa bank_mask:0xf
	v_add_f32_dpp v242, v242, v242 row_bcast:15 row_mask:0xa bank_mask:0xf
	v_add_f32_dpp v243, v243, v243 row_bcast:15 row_mask:0xa bank_mask:0xf
	v_add_f32_dpp v236, v236, v236 row_bcast:31 row_mask:0xc bank_mask:0xf
	v_add_f32_dpp v237, v237, v237 row_bcast:31 row_mask:0xc bank_mask:0xf
	v_add_f32_dpp v238, v238, v238 row_bcast:31 row_mask:0xc bank_mask:0xf
	v_add_f32_dpp v239, v239, v239 row_bcast:31 row_mask:0xc bank_mask:0xf
	v_add_f32_dpp v240, v240, v240 row_bcast:31 row_mask:0xc bank_mask:0xf
	v_add_f32_dpp v241, v241, v241 row_bcast:31 row_mask:0xc bank_mask:0xf
	v_add_f32_dpp v242, v242, v242 row_bcast:31 row_mask:0xc bank_mask:0xf
	v_add_f32_dpp v243, v243, v243 row_bcast:31 row_mask:0xc bank_mask:0xf
	v_readlane_b32 s72, v236, 63
	v_readlane_b32 s73, v237, 63
	v_readlane_b32 s74, v238, 63
	v_readlane_b32 s75, v239, 63
	v_readlane_b32 s76, v240, 63
	v_readlane_b32 s77, v241, 63
	v_readlane_b32 s78, v242, 63
	v_readlane_b32 s79, v243, 63
	v_writelane_b32 v217, s72, 0
	v_writelane_b32 v217, s73, 8
	v_writelane_b32 v217, s74, 16
	v_writelane_b32 v217, s75, 24
	v_writelane_b32 v217, s76, 32
	v_writelane_b32 v217, s77, 40
	v_writelane_b32 v217, s78, 48
	v_writelane_b32 v217, s79, 56
	s_and_saveexec_b64 s[8:9], vcc
	s_cbranch_execz .LBB0_167
	v_lshlrev_b64 v[178:179], 5, v[194:195]
	v_lshl_add_u64 v[178:179], v[200:201], 0, v[178:179]
	global_store_dword v[178:179], v217, off
	s_branch .LBB0_167
